# GEMM K loop: per-segment s_setprio flips removed, one static s_setprio 1 for the second (younger) four-wave half per gemm call
# speedup vs baseline: 1.0924x; 1.0038x over previous
; #define PG8_STAGE(bufoff, gbase, voff) do { _Pragma("unroll") for (int _i = 0; _i < 2; ++_i) \
;         __builtin_amdgcn_global_load_lds((const unsigned*)((const char*)(gbase) + (voff)[_i]), (LAS unsigned*)(lds + (bufoff) + ldsw + _i * 8192), 16, 0, 0); } while (0)
; #define PG8_WAIT_V(n) asm volatile("s_waitcnt vmcnt(" #n ")" ::: "memory")
; #define PG8_BAR __builtin_amdgcn_s_barrier()
; template <class Epi>
; __device__ __forceinline__ void gemm_phase(LAS unsigned char* lds, const Gemm g, const Epi& E) {
;     ...
;     for (int i = 0; i < 2; ++i) { int R, C; stage_rc(tid * 16 + i * 8192, R, C); const int Ra = (g.ovl == 1) ? (R >> 6) * 62 + (R & 63) : R;
;         const int Rb = g.perm ? ((R & ~31) + 8 * ((R & 15) >> 2) + 4 * ((R >> 4) & 1) + (R & 3)) : R;
;         voffA[i] = (unsigned)(Ra * g.lda + C) * 2u; voffB[i] = (unsigned)(Rb * g.ldb + C) * 2u; }
;     const size_t kstep = (size_t)(BK * 2);
;     const size_t hstepA = (size_t)((g.ovl == 1) ? 124 : HALF) * g.lda * 2, hstepB = (size_t)HALF * g.ldb * 2;
;     const size_t tstepA = 2 * hstepA, tstepB = 2 * hstepB;
;     const unsigned ldsw = (unsigned)wid * 1024u;
;     const int aoff = lds_byte(wr * 64 + fr, fq * 8), boff = lds_byte(wc * 32 + fr, fq * 8);
;     ...
;     const bool split = (g.ovl == 2); const size_t koff = (size_t)g.K * 2;
;     Unit cur, nxt; int ui = 0, chalf = 0, nhalf = 0;
;     if (!S.next(0, cur)) return;
;     f32x4 acc[2][2][4][2];
; #pragma unroll
;     for (int a = 0; a < 2; ++a)
; #pragma unroll
;         for (int b = 0; b < 2; ++b)
; #pragma unroll
;             for (int m = 0; m < 4; ++m)
; #pragma unroll
;                 for (int n = 0; n < 2; ++n) acc[a][b][m][n] = (f32x4){0.f, 0.f, 0.f, 0.f};
;     bf16x8 At[4][2], B0[2][2], B1[2][2];
;     const char* cA = (const char*)g.A + (size_t)cur.pm * tstepA; const char* cB = (const char*)g.Bt + (size_t)cur.pn * tstepB;
;     PG8_STAGE(PG8_SB(0, 0), cB, voffB); PG8_STAGE(PG8_SA(0, 0), cA, voffA); PG8_STAGE(PG8_SB(0, 1), cB + hstepB, voffB); PG8_STAGE(PG8_SA(0, 1), cA + hstepA, voffA);
;     if (wr == 1) PG8_BAR;
;     PG8_WAIT_V(4); PG8_BAR;
.LBB0_262:
	v_lshlrev_b32_e32 v10, 6, v10
	v_mul_i32_i24_e32 v5, 64, v5
	v_lshlrev_b32_e32 v7, 5, v7
	v_sub_u32_e32 v8, v8, v10
	v_lshlrev_b32_e32 v2, 5, v2
	v_sub_u32_e32 v3, v3, v5
	v_and_b32_e32 v7, 32, v7
	v_ashrrev_i16_sdwa v8, v185, sext(v8) dst_sel:DWORD dst_unused:UNUSED_PAD src0_sel:DWORD src1_sel:BYTE_0
	v_and_b32_e32 v2, 32, v2
	v_ashrrev_i16_sdwa v3, v185, sext(v3) dst_sel:DWORD dst_unused:UNUSED_PAD src0_sel:DWORD src1_sel:BYTE_0
	v_add_u32_sdwa v7, v7, sext(v8) dst_sel:DWORD dst_unused:UNUSED_PAD src0_sel:DWORD src1_sel:WORD_0
	v_lshrrev_b32_e32 v8, 6, v9
	v_and_b32_e32 v10, 63, v9
	v_add_u32_sdwa v2, v2, sext(v3) dst_sel:DWORD dst_unused:UNUSED_PAD src0_sel:DWORD src1_sel:WORD_0
	v_lshrrev_b32_e32 v3, 6, v4
	v_and_b32_e32 v5, 63, v4
	v_mad_i32_i24 v8, v8, 62, v10
	s_mul_i32 s8, s4, s2
	s_mov_b32 s9, s29
	v_mad_i32_i24 v3, v3, 62, v5
	v_cndmask_b32_e64 v8, v9, v8, s[0:1]
	s_lshl_b64 s[26:27], s[8:9], 2
	v_cndmask_b32_e64 v3, v4, v3, s[0:1]
	s_ashr_i32 s0, s61, 31
	s_mul_i32 s0, s26, s0
	s_mul_hi_u32 s1, s26, s61
	s_add_i32 s0, s1, s0
	s_lshr_b32 s1, s8, 30
	v_mul_lo_u32 v8, v8, s2
	v_mul_lo_u32 v3, v3, s2
	s_mul_i32 s1, s1, s61
	v_add_lshl_u32 v164, v8, v7, 1
	v_mul_lo_u32 v8, v11, s2
	s_lshl_b32 s49, s2, 8
	s_lshl_b32 s6, s2, 9
	v_add_lshl_u32 v168, v3, v2, 1
	v_mul_lo_u32 v3, v6, s2
	s_add_i32 s2, s0, s1
	s_ashr_i32 s0, s44, 31
	s_ashr_i32 s12, s17, 6
	s_mul_i32 s0, s6, s0
	s_mul_hi_u32 s1, s6, s44
	s_ashr_i32 s5, s17, 8
	s_cmp_lg_u32 s5, 0
	s_cbranch_scc0 .Lgemm_prio_lo
	s_setprio 1
.Lgemm_prio_lo:
	s_lshl_b64 s[34:35], s[8:9], 1
	s_lshl_b32 s7, s12, 10
	s_add_i32 s1, s1, s0
	s_mul_i32 s0, s6, s44
	s_add_u32 s0, s94, s0
	s_addc_u32 s1, s95, s1
	s_lshr_b32 s98, s44, 2
	s_lshl_b32 s98, s98, 8
	s_cmp_eq_u32 s53, 3
	s_cselect_b32 s98, s98, 0
	s_add_u32 s0, s0, s98
	s_addc_u32 s1, s1, 0
	s_add_i32 s8, s7, 0
	v_add_lshl_u32 v170, v3, v2, 1
	s_add_i32 m0, s8, 0x10000
	s_mul_i32 s4, s26, s61
	global_load_lds_dwordx4 v170, s[0:1]
	s_add_i32 m0, s8, 0x12000
	v_add_lshl_u32 v166, v8, v7, 1
	s_add_u32 s14, s96, s4
	v_writelane_b32 v249, s20, 56
	global_load_lds_dwordx4 v166, s[0:1]
	s_addc_u32 s15, s97, s2
	s_add_u32 s14, s14, s98
	s_addc_u32 s15, s15, 0
	s_mov_b32 m0, s8
	s_add_i32 s9, s8, 0x2000
	v_writelane_b32 v249, s21, 57
	global_load_lds_dwordx4 v168, s[14:15]
	s_mov_b32 m0, s9
	s_add_u32 s16, s0, s49
	v_writelane_b32 v249, s17, 58
	global_load_lds_dwordx4 v164, s[14:15]
	s_addc_u32 s17, s1, 0
	s_add_i32 m0, s8, 0x14000
	v_mov_b32_e32 v171, v1
	global_load_lds_dwordx4 v170, s[16:17]
	s_add_i32 m0, s8, 0x16000
	s_add_u32 s18, s14, s34
	s_addc_u32 s19, s15, s35
	s_add_i32 s2, s8, 0x4000
	global_load_lds_dwordx4 v166, s[16:17]
	s_mov_b32 m0, s2
	s_add_i32 s86, s8, 0x6000
	global_load_lds_dwordx4 v168, s[18:19]
	s_mov_b32 m0, s86
	v_mov_b32_e32 v167, v1
	global_load_lds_dwordx4 v164, s[18:19]
	v_mov_b32_e32 v169, v1
	v_mov_b32_e32 v165, v1
	v_lshl_add_u64 v[12:13], s[0:1], 0, v[170:171]
	v_lshl_add_u64 v[10:11], s[0:1], 0, v[166:167]
	v_lshl_add_u64 v[8:9], s[14:15], 0, v[168:169]
	v_lshl_add_u64 v[6:7], s[14:15], 0, v[164:165]
	v_lshl_add_u64 v[4:5], s[16:17], 0, v[170:171]
	s_cmp_lg_u32 s5, 1
	v_lshl_add_u64 v[2:3], s[16:17], 0, v[166:167]
	s_cbranch_scc1 .LBB0_264
	s_barrier

; #define PG8_STAGE(bufoff, gbase, voff) do { _Pragma("unroll") for (int _i = 0; _i < 2; ++_i) \
;         __builtin_amdgcn_global_load_lds((const unsigned*)((const char*)(gbase) + (voff)[_i]), (LAS unsigned*)(lds + (bufoff) + ldsw + _i * 8192), 16, 0, 0); } while (0)
; #define PG8_LDA(dst, b, h) do { _Pragma("unroll") for (int m = 0; m < 4; ++m) _Pragma("unroll") for (int k = 0; k < 2; ++k) dst[m][k] = *(const LAS bf16x8*)(lds + PG8_SA(b, h) + aoff + m * 2048 + k * 1024); } while (0)
; #define PG8_LDB(dst, b, h) do { _Pragma("unroll") for (int n = 0; n < 2; ++n) _Pragma("unroll") for (int k = 0; k < 2; ++k) dst[n][k] = *(const LAS bf16x8*)(lds + PG8_SB(b, h) + boff + n * 2048 + k * 1024); } while (0)
; #define PG8_MMA(ai, bj, At, Bt) do { __builtin_amdgcn_s_setprio(1); _Pragma("unroll") for (int m = 0; m < 4; ++m) _Pragma("unroll") for (int n = 0; n < 2; ++n) _Pragma("unroll") for (int k = 0; k < 2; ++k) \
;         acc[ai][bj][m][n] = __builtin_amdgcn_mfma_f32_16x16x32_bf16(Bt[n][k], At[m][k], acc[ai][bj][m][n], 0, 0, 0); __builtin_amdgcn_s_setprio(0); } while (0)
; #define PG8_WAIT_L(n) asm volatile("s_waitcnt lgkmcnt(" #n ")" ::: "memory")
; #define PG8_BAR __builtin_amdgcn_s_barrier()
; #define PG8_SCHED __builtin_amdgcn_sched_barrier(0)
; template <class Epi>
; __device__ __forceinline__ void gemm_phase(LAS unsigned char* lds, const Gemm g, const Epi& E) {
;     ...
;         for (int t = 0; t < nt; t += 2) {
;             const bool last = (t == nt - 2);
;             const char* a1 = cA + (size_t)(t + 1) * kstep;
;             const char* a2 = last ? nA : cA + (size_t)(t + 2) * kstep; const char* b2 = last ? nB : cB + (size_t)(t + 2) * kstep;
;             const char* a3 = a2 + kstep; const char* b3 = b2 + kstep;
;             PG8_LDB(B0, 0, 0); PG8_SCHED; PG8_LDA(At, 0, 0); PG8_STAGE(PG8_SA(1, 1), a1 + hstepA, voffA);
;             PG8_WAIT_L(8); PG8_BAR; PG8_WAIT_L(0); PG8_MMA(0, 0, At, B0); PG8_BAR; PG8_SCHED;
;             PG8_LDB(B1, 0, 1); PG8_STAGE(PG8_SB(0, 0), b2, voffB);
;             PG8_BAR; PG8_WAIT_L(0); PG8_MMA(0, 1, At, B1); PG8_BAR;
;             PG8_LDA(At, 0, 1); PG8_STAGE(PG8_SA(0, 0), a2, voffA);
;             PG8_BAR; PG8_WAIT_L(0); PG8_MMA(1, 0, At, B0); PG8_BAR; PG8_SCHED;
.LBB0_278:
	s_add_i32 s19, s12, 2
	s_add_u32 s14, s0, 0x80
	s_addc_u32 s13, s1, 0
	s_add_i32 s20, 0, 0x10000
	v_add_u32_e32 v0, s20, v197
	ds_read_b128 v[132:135], v0
	ds_read_b128 v[136:139], v0 offset:1024
	ds_read_b128 v[140:143], v0 offset:2048
	ds_read_b128 v[144:147], v0 offset:3072
	s_cmp_eq_u32 s85, s12
	s_cselect_b32 s12, s22, s14
	s_cselect_b32 s13, s23, s13
	s_cselect_b32 s15, s5, s18
	s_cselect_b32 s14, s4, s17
	v_lshl_add_u64 v[2:3], s[0:1], 0, v[174:175]
	s_add_i32 m0, s8, 0xc000
	ds_read_b128 v[148:151], v205
	ds_read_b128 v[152:155], v205 offset:1024
	ds_read_b128 v[156:159], v205 offset:2048
	ds_read_b128 v[160:163], v205 offset:3072
	ds_read_b128 v[176:179], v205 offset:4096
	ds_read_b128 v[206:209], v205 offset:5120
	ds_read_b128 v[210:213], v205 offset:6144
	ds_read_b128 v[214:217], v205 offset:7168
	global_load_lds_dwordx4 v[2:3], off
	v_lshl_add_u64 v[2:3], s[0:1], 0, v[172:173]
	s_add_i32 m0, s8, 0xe000
	s_nop 0
	global_load_lds_dwordx4 v[2:3], off
	s_waitcnt lgkmcnt(8)
	s_barrier
	s_waitcnt lgkmcnt(0)
	s_waitcnt lgkmcnt(0)
	v_mfma_f32_16x16x32_bf16 v[48:51], v[132:135], v[148:151], v[48:51]
	v_mfma_f32_16x16x32_bf16 v[52:55], v[140:143], v[148:151], v[52:55]
	v_mfma_f32_16x16x32_bf16 v[56:59], v[132:135], v[156:159], v[56:59]
	v_mfma_f32_16x16x32_bf16 v[60:63], v[140:143], v[156:159], v[60:63]
	v_mfma_f32_16x16x32_bf16 v[64:67], v[132:135], v[176:179], v[64:67]
	v_mfma_f32_16x16x32_bf16 v[68:71], v[140:143], v[176:179], v[68:71]
	v_mfma_f32_16x16x32_bf16 v[72:75], v[132:135], v[210:213], v[72:75]
	v_mfma_f32_16x16x32_bf16 v[76:79], v[140:143], v[210:213], v[76:79]
	v_mfma_f32_16x16x32_bf16 v[48:51], v[136:139], v[152:155], v[48:51]
	v_mfma_f32_16x16x32_bf16 v[52:55], v[144:147], v[152:155], v[52:55]
	v_mfma_f32_16x16x32_bf16 v[56:59], v[136:139], v[160:163], v[56:59]
	v_mfma_f32_16x16x32_bf16 v[60:63], v[144:147], v[160:163], v[60:63]
	v_mfma_f32_16x16x32_bf16 v[64:67], v[136:139], v[206:209], v[64:67]
	v_mfma_f32_16x16x32_bf16 v[68:71], v[144:147], v[206:209], v[68:71]
	v_mfma_f32_16x16x32_bf16 v[72:75], v[136:139], v[214:217], v[72:75]
	v_mfma_f32_16x16x32_bf16 v[76:79], v[144:147], v[214:217], v[76:79]
	s_barrier
	s_add_i32 s21, 0, 0x14000
	s_add_i32 s20, s20, s7
	v_add_u32_e32 v0, s21, v197
	v_lshl_add_u64 v[234:235], s[14:15], 0, v[170:171]
	s_mov_b32 m0, s20
	ds_read_b128 v[218:221], v0
	ds_read_b128 v[222:225], v0 offset:1024
	ds_read_b128 v[226:229], v0 offset:2048
	ds_read_b128 v[230:233], v0 offset:3072
	global_load_lds_dwordx4 v[234:235], off
	v_lshl_add_u64 v[236:237], s[14:15], 0, v[166:167]
	s_add_i32 m0, s20, 0x2000
	s_nop 0
	global_load_lds_dwordx4 v[236:237], off
	s_barrier
	s_waitcnt lgkmcnt(0)
	s_waitcnt lgkmcnt(0)
	v_mfma_f32_16x16x32_bf16 v[80:83], v[218:221], v[148:151], v[80:83]
	v_mfma_f32_16x16x32_bf16 v[84:87], v[226:229], v[148:151], v[84:87]
	v_mfma_f32_16x16x32_bf16 v[88:91], v[218:221], v[156:159], v[88:91]
	v_mfma_f32_16x16x32_bf16 v[92:95], v[226:229], v[156:159], v[92:95]
	v_mfma_f32_16x16x32_bf16 v[96:99], v[218:221], v[176:179], v[96:99]
	v_mfma_f32_16x16x32_bf16 v[100:103], v[226:229], v[176:179], v[100:103]
	v_mfma_f32_16x16x32_bf16 v[104:107], v[218:221], v[210:213], v[104:107]
	v_mfma_f32_16x16x32_bf16 v[108:111], v[226:229], v[210:213], v[108:111]
	v_mfma_f32_16x16x32_bf16 v[80:83], v[222:225], v[152:155], v[80:83]
	v_mfma_f32_16x16x32_bf16 v[84:87], v[230:233], v[152:155], v[84:87]
	v_mfma_f32_16x16x32_bf16 v[88:91], v[222:225], v[160:163], v[88:91]
	v_mfma_f32_16x16x32_bf16 v[92:95], v[230:233], v[160:163], v[92:95]
	v_mfma_f32_16x16x32_bf16 v[96:99], v[222:225], v[206:209], v[96:99]
	v_mfma_f32_16x16x32_bf16 v[100:103], v[230:233], v[206:209], v[100:103]
	v_mfma_f32_16x16x32_bf16 v[104:107], v[222:225], v[214:217], v[104:107]
	v_mfma_f32_16x16x32_bf16 v[108:111], v[230:233], v[214:217], v[108:111]
	s_mov_b32 m0, s8
	v_lshl_add_u64 v[238:239], s[12:13], 0, v[168:169]
	s_barrier
	ds_read_b128 v[148:151], v205 offset:16384
	ds_read_b128 v[152:155], v205 offset:17408
	ds_read_b128 v[156:159], v205 offset:18432
	ds_read_b128 v[160:163], v205 offset:19456
	ds_read_b128 v[176:179], v205 offset:20480
	ds_read_b128 v[206:209], v205 offset:21504
	ds_read_b128 v[210:213], v205 offset:22528
	ds_read_b128 v[214:217], v205 offset:23552
	global_load_lds_dwordx4 v[238:239], off
	v_lshl_add_u64 v[240:241], s[12:13], 0, v[164:165]
	s_mov_b32 m0, s9
	s_nop 0
	global_load_lds_dwordx4 v[240:241], off
	s_barrier
	s_waitcnt lgkmcnt(0)
	s_waitcnt lgkmcnt(0)
	v_mfma_f32_16x16x32_bf16 v[112:115], v[132:135], v[148:151], v[112:115]
	v_mfma_f32_16x16x32_bf16 v[116:119], v[140:143], v[148:151], v[116:119]
	v_mfma_f32_16x16x32_bf16 v[120:123], v[132:135], v[156:159], v[120:123]
	v_mfma_f32_16x16x32_bf16 v[124:127], v[140:143], v[156:159], v[124:127]
	v_mfma_f32_16x16x32_bf16 v[128:131], v[132:135], v[176:179], v[128:131]
	v_mfma_f32_16x16x32_bf16 v[36:39], v[140:143], v[176:179], v[36:39]
	v_mfma_f32_16x16x32_bf16 v[40:43], v[132:135], v[210:213], v[40:43]
	v_mfma_f32_16x16x32_bf16 v[44:47], v[140:143], v[210:213], v[44:47]
	v_mfma_f32_16x16x32_bf16 v[112:115], v[136:139], v[152:155], v[112:115]
	v_mfma_f32_16x16x32_bf16 v[116:119], v[144:147], v[152:155], v[116:119]
	v_mfma_f32_16x16x32_bf16 v[120:123], v[136:139], v[160:163], v[120:123]
	v_mfma_f32_16x16x32_bf16 v[124:127], v[144:147], v[160:163], v[124:127]
	v_mfma_f32_16x16x32_bf16 v[128:131], v[136:139], v[206:209], v[128:131]
	v_mfma_f32_16x16x32_bf16 v[36:39], v[144:147], v[206:209], v[36:39]
	v_mfma_f32_16x16x32_bf16 v[40:43], v[136:139], v[214:217], v[40:43]
	v_mfma_f32_16x16x32_bf16 v[44:47], v[144:147], v[214:217], v[44:47]
	s_barrier
; #define PG8_STAGE(bufoff, gbase, voff) do { _Pragma("unroll") for (int _i = 0; _i < 2; ++_i) \
;         __builtin_amdgcn_global_load_lds((const unsigned*)((const char*)(gbase) + (voff)[_i]), (LAS unsigned*)(lds + (bufoff) + ldsw + _i * 8192), 16, 0, 0); } while (0)
; #define PG8_LDA(dst, b, h) do { _Pragma("unroll") for (int m = 0; m < 4; ++m) _Pragma("unroll") for (int k = 0; k < 2; ++k) dst[m][k] = *(const LAS bf16x8*)(lds + PG8_SA(b, h) + aoff + m * 2048 + k * 1024); } while (0)
; #define PG8_LDB(dst, b, h) do { _Pragma("unroll") for (int n = 0; n < 2; ++n) _Pragma("unroll") for (int k = 0; k < 2; ++k) dst[n][k] = *(const LAS bf16x8*)(lds + PG8_SB(b, h) + boff + n * 2048 + k * 1024); } while (0)
; #define PG8_MMA(ai, bj, At, Bt) do { __builtin_amdgcn_s_setprio(1); _Pragma("unroll") for (int m = 0; m < 4; ++m) _Pragma("unroll") for (int n = 0; n < 2; ++n) _Pragma("unroll") for (int k = 0; k < 2; ++k) \
;         acc[ai][bj][m][n] = __builtin_amdgcn_mfma_f32_16x16x32_bf16(Bt[n][k], At[m][k], acc[ai][bj][m][n], 0, 0, 0); __builtin_amdgcn_s_setprio(0); } while (0)
; #define PG8_WAIT_V(n) asm volatile("s_waitcnt vmcnt(" #n ")" ::: "memory")
; #define PG8_WAIT_L(n) asm volatile("s_waitcnt lgkmcnt(" #n ")" ::: "memory")
; #define PG8_BAR __builtin_amdgcn_s_barrier()
; #define PG8_SCHED __builtin_amdgcn_sched_barrier(0)
; template <class Epi>
; __device__ __forceinline__ void gemm_phase(LAS unsigned char* lds, const Gemm g, const Epi& E) {
;     ...
;             PG8_STAGE(PG8_SB(0, 1), b2 + hstepB, voffB);
;             PG8_WAIT_V(6); PG8_BAR; PG8_MMA(1, 1, At, B1); PG8_BAR;
;             PG8_LDB(B0, 1, 0); PG8_SCHED; PG8_LDA(At, 1, 0); PG8_STAGE(PG8_SA(0, 1), a2 + hstepA, voffA);
;             PG8_WAIT_L(8); PG8_BAR; PG8_WAIT_L(0); PG8_MMA(0, 0, At, B0); PG8_BAR; PG8_SCHED;
;             PG8_LDB(B1, 1, 1); PG8_STAGE(PG8_SB(1, 0), b3, voffB);
;             PG8_BAR; PG8_WAIT_L(0); PG8_MMA(0, 1, At, B1); PG8_BAR;
;             PG8_LDA(At, 1, 1); PG8_STAGE(PG8_SA(1, 0), a3, voffA);
	s_add_u32 s14, s14, s49
	s_addc_u32 s15, s15, 0
	s_add_i32 s20, s21, s7
	v_lshl_add_u64 v[242:243], s[14:15], 0, v[170:171]
	s_mov_b32 m0, s20
	v_lshl_add_u64 v[244:245], s[14:15], 0, v[166:167]
	global_load_lds_dwordx4 v[242:243], off
	s_add_i32 m0, s20, 0x2000
	s_nop 0
	global_load_lds_dwordx4 v[244:245], off
	s_waitcnt vmcnt(6)
	s_barrier
	v_mfma_f32_16x16x32_bf16 v[2:5], v[218:221], v[148:151], v[4:7]
	v_mfma_f32_16x16x32_bf16 v[6:9], v[226:229], v[148:151], v[8:11]
	v_mfma_f32_16x16x32_bf16 v[12:15], v[218:221], v[156:159], v[12:15]
	v_mfma_f32_16x16x32_bf16 v[16:19], v[226:229], v[156:159], v[16:19]
	v_mfma_f32_16x16x32_bf16 v[20:23], v[218:221], v[176:179], v[20:23]
	v_mfma_f32_16x16x32_bf16 v[24:27], v[226:229], v[176:179], v[24:27]
	v_mfma_f32_16x16x32_bf16 v[28:31], v[218:221], v[210:213], v[28:31]
	v_mfma_f32_16x16x32_bf16 v[32:35], v[226:229], v[210:213], v[32:35]
	v_mfma_f32_16x16x32_bf16 v[2:5], v[222:225], v[152:155], v[2:5]
	v_mfma_f32_16x16x32_bf16 v[8:11], v[230:233], v[152:155], v[6:9]
	v_mfma_f32_16x16x32_bf16 v[12:15], v[222:225], v[160:163], v[12:15]
	v_mfma_f32_16x16x32_bf16 v[16:19], v[230:233], v[160:163], v[16:19]
	v_mfma_f32_16x16x32_bf16 v[20:23], v[222:225], v[206:209], v[20:23]
	v_mfma_f32_16x16x32_bf16 v[24:27], v[230:233], v[206:209], v[24:27]
	v_mfma_f32_16x16x32_bf16 v[28:31], v[222:225], v[214:217], v[28:31]
	v_mfma_f32_16x16x32_bf16 v[32:35], v[230:233], v[214:217], v[32:35]
	s_add_i32 s14, 0, 0x18000
	v_add_u32_e32 v0, s14, v197
	s_barrier
	ds_read_b128 v[132:135], v0
	ds_read_b128 v[136:139], v0 offset:1024
	ds_read_b128 v[140:143], v0 offset:2048
	ds_read_b128 v[144:147], v0 offset:3072
	s_add_u32 s12, s12, s34
	s_addc_u32 s13, s13, s35
	s_mov_b32 m0, s2
	v_lshl_add_u64 v[6:7], s[12:13], 0, v[168:169]
	ds_read_b128 v[148:151], v205 offset:32768
	ds_read_b128 v[152:155], v205 offset:33792
	ds_read_b128 v[156:159], v205 offset:34816
	ds_read_b128 v[160:163], v205 offset:35840
	ds_read_b128 v[176:179], v205 offset:36864
	ds_read_b128 v[206:209], v205 offset:37888
	ds_read_b128 v[210:213], v205 offset:38912
	ds_read_b128 v[214:217], v205 offset:39936
	global_load_lds_dwordx4 v[6:7], off
	v_lshl_add_u64 v[6:7], s[12:13], 0, v[164:165]
	s_mov_b32 m0, s86
	s_nop 0
	global_load_lds_dwordx4 v[6:7], off
	s_waitcnt lgkmcnt(8)
	s_barrier
	s_waitcnt lgkmcnt(0)
	s_waitcnt lgkmcnt(0)
	v_mfma_f32_16x16x32_bf16 v[48:51], v[132:135], v[148:151], v[48:51]
	v_mfma_f32_16x16x32_bf16 v[52:55], v[140:143], v[148:151], v[52:55]
	v_mfma_f32_16x16x32_bf16 v[56:59], v[132:135], v[156:159], v[56:59]
	v_mfma_f32_16x16x32_bf16 v[60:63], v[140:143], v[156:159], v[60:63]
	v_mfma_f32_16x16x32_bf16 v[64:67], v[132:135], v[176:179], v[64:67]
	v_mfma_f32_16x16x32_bf16 v[68:71], v[140:143], v[176:179], v[68:71]
	v_mfma_f32_16x16x32_bf16 v[72:75], v[132:135], v[210:213], v[72:75]
	v_mfma_f32_16x16x32_bf16 v[76:79], v[140:143], v[210:213], v[76:79]
	v_mfma_f32_16x16x32_bf16 v[48:51], v[136:139], v[152:155], v[48:51]
	v_mfma_f32_16x16x32_bf16 v[52:55], v[144:147], v[152:155], v[52:55]
	v_mfma_f32_16x16x32_bf16 v[56:59], v[136:139], v[160:163], v[56:59]
	v_mfma_f32_16x16x32_bf16 v[60:63], v[144:147], v[160:163], v[60:63]
	v_mfma_f32_16x16x32_bf16 v[64:67], v[136:139], v[206:209], v[64:67]
	v_mfma_f32_16x16x32_bf16 v[68:71], v[144:147], v[206:209], v[68:71]
	v_mfma_f32_16x16x32_bf16 v[72:75], v[136:139], v[214:217], v[72:75]
	v_mfma_f32_16x16x32_bf16 v[76:79], v[144:147], v[214:217], v[76:79]
	s_barrier
	s_add_i32 s12, 0, 0x1c000
	s_add_i32 s13, s14, s7
	v_add_u32_e32 v0, s12, v197
	v_lshl_add_u64 v[6:7], v[234:235], 0, s[36:37]
	s_mov_b32 m0, s13
	ds_read_b128 v[218:221], v0
	ds_read_b128 v[222:225], v0 offset:1024
	ds_read_b128 v[226:229], v0 offset:2048
	ds_read_b128 v[230:233], v0 offset:3072
	global_load_lds_dwordx4 v[6:7], off
	v_lshl_add_u64 v[6:7], v[236:237], 0, s[36:37]
	s_add_i32 m0, s13, 0x2000
	s_nop 0
	global_load_lds_dwordx4 v[6:7], off
	s_barrier
	s_waitcnt lgkmcnt(0)
	s_waitcnt lgkmcnt(0)
	v_mfma_f32_16x16x32_bf16 v[80:83], v[218:221], v[148:151], v[80:83]
	v_mfma_f32_16x16x32_bf16 v[84:87], v[226:229], v[148:151], v[84:87]
	v_mfma_f32_16x16x32_bf16 v[88:91], v[218:221], v[156:159], v[88:91]
	v_mfma_f32_16x16x32_bf16 v[92:95], v[226:229], v[156:159], v[92:95]
	v_mfma_f32_16x16x32_bf16 v[96:99], v[218:221], v[176:179], v[96:99]
	v_mfma_f32_16x16x32_bf16 v[100:103], v[226:229], v[176:179], v[100:103]
	v_mfma_f32_16x16x32_bf16 v[104:107], v[218:221], v[210:213], v[104:107]
	v_mfma_f32_16x16x32_bf16 v[108:111], v[226:229], v[210:213], v[108:111]
	v_mfma_f32_16x16x32_bf16 v[80:83], v[222:225], v[152:155], v[80:83]
	v_mfma_f32_16x16x32_bf16 v[84:87], v[230:233], v[152:155], v[84:87]
	v_mfma_f32_16x16x32_bf16 v[88:91], v[222:225], v[160:163], v[88:91]
	v_mfma_f32_16x16x32_bf16 v[92:95], v[230:233], v[160:163], v[92:95]
	v_mfma_f32_16x16x32_bf16 v[96:99], v[222:225], v[206:209], v[96:99]
	v_mfma_f32_16x16x32_bf16 v[100:103], v[230:233], v[206:209], v[100:103]
	v_mfma_f32_16x16x32_bf16 v[104:107], v[222:225], v[214:217], v[104:107]
	v_mfma_f32_16x16x32_bf16 v[108:111], v[230:233], v[214:217], v[108:111]
	s_mov_b32 m0, s38
	v_lshl_add_u64 v[6:7], v[238:239], 0, s[36:37]
	s_barrier
	ds_read_b128 v[148:151], v205 offset:49152
	ds_read_b128 v[152:155], v205 offset:50176
	ds_read_b128 v[156:159], v205 offset:51200
	ds_read_b128 v[160:163], v205 offset:52224
	ds_read_b128 v[176:179], v205 offset:53248
	ds_read_b128 v[206:209], v205 offset:54272
	ds_read_b128 v[210:213], v205 offset:55296
	ds_read_b128 v[214:217], v205 offset:56320
	global_load_lds_dwordx4 v[6:7], off
	v_lshl_add_u64 v[6:7], v[240:241], 0, s[36:37]
	s_mov_b32 m0, s39
	s_nop 0
	global_load_lds_dwordx4 v[6:7], off
	s_barrier
; __device__ __forceinline__ unsigned pack2(float lo, float hi) { return (unsigned)f2bf(lo) | ((unsigned)f2bf(hi) << 16); }
; #define PG8_STAGE(bufoff, gbase, voff) do { _Pragma("unroll") for (int _i = 0; _i < 2; ++_i) \
;         __builtin_amdgcn_global_load_lds((const unsigned*)((const char*)(gbase) + (voff)[_i]), (LAS unsigned*)(lds + (bufoff) + ldsw + _i * 8192), 16, 0, 0); } while (0)
; #define PG8_MMA(ai, bj, At, Bt) do { __builtin_amdgcn_s_setprio(1); _Pragma("unroll") for (int m = 0; m < 4; ++m) _Pragma("unroll") for (int n = 0; n < 2; ++n) _Pragma("unroll") for (int k = 0; k < 2; ++k) \
;         acc[ai][bj][m][n] = __builtin_amdgcn_mfma_f32_16x16x32_bf16(Bt[n][k], At[m][k], acc[ai][bj][m][n], 0, 0, 0); __builtin_amdgcn_s_setprio(0); } while (0)
; #define PG8_WAIT_V(n) asm volatile("s_waitcnt vmcnt(" #n ")" ::: "memory")
; #define PG8_WAIT_L(n) asm volatile("s_waitcnt lgkmcnt(" #n ")" ::: "memory")
; #define PG8_BAR __builtin_amdgcn_s_barrier()
; #define PG8_SCHED __builtin_amdgcn_sched_barrier(0)
; template <class Epi>
; __device__ __forceinline__ void gemm_phase(LAS unsigned char* lds, const Gemm g, const Epi& E) {
;     ...
;             PG8_BAR; PG8_WAIT_L(0); PG8_MMA(1, 0, At, B0); PG8_BAR; PG8_SCHED;
;             PG8_STAGE(PG8_SB(1, 1), b3 + hstepB, voffB);
;             PG8_WAIT_V(6); PG8_BAR; PG8_MMA(1, 1, At, B1); PG8_BAR;
;     __device__ __forceinline__ void operator()(const f32x4 (&acc)[2][2][4][2], const Unit& u, int wr, int wc, int fr, int fq) const {
;         EPIP_ROWS( uint4 o; o.x = pack2(v0[0], v0[1]); o.y = pack2(v0[2], v0[3]); o.z = pack2(v1[0], v1[1]); o.w = pack2(v1[2], v1[3]); *(uint4*)(O + row * ldc + col8 + co) = o; )
	s_waitcnt lgkmcnt(0)
	s_waitcnt lgkmcnt(0)
	v_mfma_f32_16x16x32_bf16 v[112:115], v[132:135], v[148:151], v[112:115]
	v_mfma_f32_16x16x32_bf16 v[116:119], v[140:143], v[148:151], v[116:119]
	v_mfma_f32_16x16x32_bf16 v[120:123], v[132:135], v[156:159], v[120:123]
	v_mfma_f32_16x16x32_bf16 v[124:127], v[140:143], v[156:159], v[124:127]
	v_mfma_f32_16x16x32_bf16 v[128:131], v[132:135], v[176:179], v[128:131]
	v_mfma_f32_16x16x32_bf16 v[36:39], v[140:143], v[176:179], v[36:39]
	v_mfma_f32_16x16x32_bf16 v[40:43], v[132:135], v[210:213], v[40:43]
	v_mfma_f32_16x16x32_bf16 v[44:47], v[140:143], v[210:213], v[44:47]
	v_mfma_f32_16x16x32_bf16 v[112:115], v[136:139], v[152:155], v[112:115]
	v_mfma_f32_16x16x32_bf16 v[116:119], v[144:147], v[152:155], v[116:119]
	v_mfma_f32_16x16x32_bf16 v[120:123], v[136:139], v[160:163], v[120:123]
	v_mfma_f32_16x16x32_bf16 v[124:127], v[144:147], v[160:163], v[124:127]
	v_mfma_f32_16x16x32_bf16 v[128:131], v[136:139], v[206:209], v[128:131]
	v_mfma_f32_16x16x32_bf16 v[36:39], v[144:147], v[206:209], v[36:39]
	v_mfma_f32_16x16x32_bf16 v[40:43], v[136:139], v[214:217], v[40:43]
	v_mfma_f32_16x16x32_bf16 v[44:47], v[144:147], v[214:217], v[44:47]
	s_barrier
	s_add_i32 s12, s12, s7
	v_lshl_add_u64 v[6:7], v[242:243], 0, s[36:37]
	s_mov_b32 m0, s12
	s_nop 0
	global_load_lds_dwordx4 v[6:7], off
	v_lshl_add_u64 v[6:7], v[244:245], 0, s[36:37]
	s_add_i32 m0, s12, 0x2000
	s_nop 0
	global_load_lds_dwordx4 v[6:7], off
	s_waitcnt vmcnt(6)
	s_barrier
	v_mfma_f32_16x16x32_bf16 v[2:5], v[218:221], v[148:151], v[2:5]
	v_mfma_f32_16x16x32_bf16 v[8:11], v[226:229], v[148:151], v[8:11]
	v_mfma_f32_16x16x32_bf16 v[12:15], v[218:221], v[156:159], v[12:15]
	v_mfma_f32_16x16x32_bf16 v[16:19], v[226:229], v[156:159], v[16:19]
	v_mfma_f32_16x16x32_bf16 v[20:23], v[218:221], v[176:179], v[20:23]
	v_mfma_f32_16x16x32_bf16 v[24:27], v[226:229], v[176:179], v[24:27]
	v_mfma_f32_16x16x32_bf16 v[28:31], v[218:221], v[210:213], v[28:31]
	v_mfma_f32_16x16x32_bf16 v[32:35], v[226:229], v[210:213], v[32:35]
	v_mfma_f32_16x16x32_bf16 v[4:7], v[222:225], v[152:155], v[2:5]
	v_mfma_f32_16x16x32_bf16 v[8:11], v[230:233], v[152:155], v[8:11]
	v_mfma_f32_16x16x32_bf16 v[12:15], v[222:225], v[160:163], v[12:15]
	v_mfma_f32_16x16x32_bf16 v[16:19], v[230:233], v[160:163], v[16:19]
	v_mfma_f32_16x16x32_bf16 v[20:23], v[222:225], v[206:209], v[20:23]
	v_mfma_f32_16x16x32_bf16 v[24:27], v[230:233], v[206:209], v[24:27]
	v_mfma_f32_16x16x32_bf16 v[28:31], v[222:225], v[214:217], v[28:31]
	v_mfma_f32_16x16x32_bf16 v[32:35], v[230:233], v[214:217], v[32:35]
	s_add_u32 s17, s17, 0x100
	s_addc_u32 s18, s18, 0
	s_add_u32 s0, s0, 0x100
	s_addc_u32 s1, s1, 0
	s_cmp_ge_u32 s19, s87
	s_mov_b32 s12, s19
	s_barrier
	s_cbranch_scc0 .LBB0_278
	s_cmp_lg_u32 s16, 0
	s_cselect_b64 s[12:13], -1, 0
	s_xor_b64 s[14:15], s[92:93], -1
	s_or_b64 s[24:25], s[14:15], s[12:13]
	s_mov_b64 s[0:1], -1
	s_and_b64 vcc, exec, s[24:25]
	s_cbranch_vccz .LBB0_352
	s_mov_b64 s[62:63], 0
	s_cmp_lt_i32 s53, 8
	s_mov_b64 s[12:13], 0
	s_cbranch_scc1 .LBB0_330
	s_mov_b64 s[14:15], -1
	s_mov_b64 s[0:1], 0
	s_cmp_gt_i32 s53, 11
	s_cbranch_scc0 .LBB0_288
	s_cmp_gt_i32 s53, 13
	s_cbranch_scc0 .LBB0_285
	s_cmp_eq_u32 s53, 14
	s_mov_b64 s[12:13], -1
	s_cbranch_scc0 .LBB0_356
	v_lshl_add_u32 v136, s61, 8, v196
	v_lshl_or_b32 v2, s44, 8, v204
	v_readlane_b32 s12, v249, 42
	v_and_b32_sdwa v133, v51, v185 dst_sel:DWORD dst_unused:UNUSED_PAD src0_sel:WORD_1 src1_sel:DWORD
	v_and_b32_sdwa v134, v49, v185 dst_sel:DWORD dst_unused:UNUSED_PAD src0_sel:WORD_1 src1_sel:DWORD
	v_ashrrev_i32_e32 v3, 31, v2
	v_readlane_b32 s13, v249, 43
	v_ashrrev_i32_e32 v137, 31, v136
	v_and_b32_sdwa v0, v50, v185 dst_sel:DWORD dst_unused:UNUSED_PAD src0_sel:WORD_1 src1_sel:DWORD
	v_and_b32_sdwa v132, v48, v185 dst_sel:DWORD dst_unused:UNUSED_PAD src0_sel:WORD_1 src1_sel:DWORD
	v_add3_u32 v133, v51, v133, s46
	v_add3_u32 v134, v49, v134, s46
	v_lshl_add_u64 v[138:139], v[2:3], 1, s[12:13]
	v_lshlrev_b64 v[2:3], 11, v[136:137]
	v_add3_u32 v132, v48, v132, s46
	v_add3_u32 v0, v50, v0, s46
	v_and_b32_e32 v133, 0xffff0000, v133
	v_and_b32_e32 v134, 0xffff0000, v134
	v_and_b32_sdwa v135, v55, v185 dst_sel:DWORD dst_unused:UNUSED_PAD src0_sel:WORD_1 src1_sel:DWORD
	v_and_b32_sdwa v137, v53, v185 dst_sel:DWORD dst_unused:UNUSED_PAD src0_sel:WORD_1 src1_sel:DWORD
	v_or_b32_sdwa v133, v133, v0 dst_sel:DWORD dst_unused:UNUSED_PAD src0_sel:DWORD src1_sel:WORD_1
	v_or_b32_sdwa v132, v134, v132 dst_sel:DWORD dst_unused:UNUSED_PAD src0_sel:DWORD src1_sel:WORD_1
	v_and_b32_sdwa v0, v54, v185 dst_sel:DWORD dst_unused:UNUSED_PAD src0_sel:WORD_1 src1_sel:DWORD
	v_and_b32_sdwa v134, v52, v185 dst_sel:DWORD dst_unused:UNUSED_PAD src0_sel:WORD_1 src1_sel:DWORD
	v_add3_u32 v135, v55, v135, s46
	v_add3_u32 v137, v53, v137, s46
	v_add3_u32 v134, v52, v134, s46
	v_add3_u32 v0, v54, v0, s46
	v_and_b32_e32 v135, 0xffff0000, v135
	v_and_b32_e32 v137, 0xffff0000, v137
	v_lshl_add_u64 v[2:3], v[138:139], 0, v[2:3]
	v_or_b32_sdwa v135, v135, v0 dst_sel:DWORD dst_unused:UNUSED_PAD src0_sel:DWORD src1_sel:WORD_1
	v_or_b32_sdwa v134, v137, v134 dst_sel:DWORD dst_unused:UNUSED_PAD src0_sel:DWORD src1_sel:WORD_1
	global_store_dwordx4 v[2:3], v[132:135], off
	v_and_b32_sdwa v0, v82, v185 dst_sel:DWORD dst_unused:UNUSED_PAD src0_sel:WORD_1 src1_sel:DWORD
	v_add3_u32 v0, v82, v0, s46
	v_and_b32_sdwa v133, v83, v185 dst_sel:DWORD dst_unused:UNUSED_PAD src0_sel:WORD_1 src1_sel:DWORD
	v_and_b32_sdwa v134, v81, v185 dst_sel:DWORD dst_unused:UNUSED_PAD src0_sel:WORD_1 src1_sel:DWORD
	v_and_b32_sdwa v132, v80, v185 dst_sel:DWORD dst_unused:UNUSED_PAD src0_sel:WORD_1 src1_sel:DWORD
; __device__ __forceinline__ unsigned pack2(float lo, float hi) { return (unsigned)f2bf(lo) | ((unsigned)f2bf(hi) << 16); }
;     __device__ __forceinline__ void operator()(const f32x4 (&acc)[2][2][4][2], const Unit& u, int wr, int wc, int fr, int fq) const {
;         EPIP_ROWS( uint4 o; o.x = pack2(v0[0], v0[1]); o.y = pack2(v0[2], v0[3]); o.z = pack2(v1[0], v1[1]); o.w = pack2(v1[2], v1[3]); *(uint4*)(O + row * ldc + col8 + co) = o; )
;     }
	v_add3_u32 v133, v83, v133, s46
	v_add3_u32 v134, v81, v134, s46
	v_add3_u32 v132, v80, v132, s46
	v_and_b32_e32 v133, 0xffff0000, v133
	v_and_b32_e32 v134, 0xffff0000, v134
	v_and_b32_sdwa v135, v87, v185 dst_sel:DWORD dst_unused:UNUSED_PAD src0_sel:WORD_1 src1_sel:DWORD
	v_and_b32_sdwa v137, v85, v185 dst_sel:DWORD dst_unused:UNUSED_PAD src0_sel:WORD_1 src1_sel:DWORD
	v_or_b32_sdwa v133, v133, v0 dst_sel:DWORD dst_unused:UNUSED_PAD src0_sel:DWORD src1_sel:WORD_1
	v_or_b32_sdwa v132, v134, v132 dst_sel:DWORD dst_unused:UNUSED_PAD src0_sel:DWORD src1_sel:WORD_1
	v_and_b32_sdwa v0, v86, v185 dst_sel:DWORD dst_unused:UNUSED_PAD src0_sel:WORD_1 src1_sel:DWORD
	v_and_b32_sdwa v134, v84, v185 dst_sel:DWORD dst_unused:UNUSED_PAD src0_sel:WORD_1 src1_sel:DWORD
	v_add3_u32 v135, v87, v135, s46
	v_add3_u32 v137, v85, v137, s46
	v_add3_u32 v134, v84, v134, s46
	v_add3_u32 v0, v86, v0, s46
	v_and_b32_e32 v135, 0xffff0000, v135
	v_and_b32_e32 v137, 0xffff0000, v137
	v_or_b32_sdwa v135, v135, v0 dst_sel:DWORD dst_unused:UNUSED_PAD src0_sel:DWORD src1_sel:WORD_1
	v_or_b32_sdwa v134, v137, v134 dst_sel:DWORD dst_unused:UNUSED_PAD src0_sel:DWORD src1_sel:WORD_1
	global_store_dwordx4 v[2:3], v[132:135], off offset:256
	v_and_b32_sdwa v0, v58, v185 dst_sel:DWORD dst_unused:UNUSED_PAD src0_sel:WORD_1 src1_sel:DWORD
	v_add3_u32 v0, v58, v0, s46
	v_or_b32_e32 v132, 16, v136
	v_ashrrev_i32_e32 v133, 31, v132
	v_lshlrev_b64 v[132:133], 11, v[132:133]
	v_lshl_add_u64 v[140:141], v[138:139], 0, v[132:133]
	v_and_b32_sdwa v133, v59, v185 dst_sel:DWORD dst_unused:UNUSED_PAD src0_sel:WORD_1 src1_sel:DWORD
	v_and_b32_sdwa v134, v57, v185 dst_sel:DWORD dst_unused:UNUSED_PAD src0_sel:WORD_1 src1_sel:DWORD
	v_and_b32_sdwa v132, v56, v185 dst_sel:DWORD dst_unused:UNUSED_PAD src0_sel:WORD_1 src1_sel:DWORD
	v_add3_u32 v133, v59, v133, s46
	v_add3_u32 v134, v57, v134, s46
	v_add3_u32 v132, v56, v132, s46
	v_and_b32_e32 v133, 0xffff0000, v133
	v_and_b32_e32 v134, 0xffff0000, v134
	v_and_b32_sdwa v135, v63, v185 dst_sel:DWORD dst_unused:UNUSED_PAD src0_sel:WORD_1 src1_sel:DWORD
	v_and_b32_sdwa v137, v61, v185 dst_sel:DWORD dst_unused:UNUSED_PAD src0_sel:WORD_1 src1_sel:DWORD
	v_or_b32_sdwa v133, v133, v0 dst_sel:DWORD dst_unused:UNUSED_PAD src0_sel:DWORD src1_sel:WORD_1
	v_or_b32_sdwa v132, v134, v132 dst_sel:DWORD dst_unused:UNUSED_PAD src0_sel:DWORD src1_sel:WORD_1
	v_and_b32_sdwa v0, v62, v185 dst_sel:DWORD dst_unused:UNUSED_PAD src0_sel:WORD_1 src1_sel:DWORD
	v_and_b32_sdwa v134, v60, v185 dst_sel:DWORD dst_unused:UNUSED_PAD src0_sel:WORD_1 src1_sel:DWORD
	v_add3_u32 v135, v63, v135, s46
	v_add3_u32 v137, v61, v137, s46
	v_add3_u32 v134, v60, v134, s46
	v_add3_u32 v0, v62, v0, s46
	v_and_b32_e32 v135, 0xffff0000, v135
	v_and_b32_e32 v137, 0xffff0000, v137
	v_or_b32_sdwa v135, v135, v0 dst_sel:DWORD dst_unused:UNUSED_PAD src0_sel:DWORD src1_sel:WORD_1
	v_or_b32_sdwa v134, v137, v134 dst_sel:DWORD dst_unused:UNUSED_PAD src0_sel:DWORD src1_sel:WORD_1
	global_store_dwordx4 v[140:141], v[132:135], off
	v_and_b32_sdwa v0, v90, v185 dst_sel:DWORD dst_unused:UNUSED_PAD src0_sel:WORD_1 src1_sel:DWORD
	v_add3_u32 v0, v90, v0, s46
	v_and_b32_sdwa v133, v91, v185 dst_sel:DWORD dst_unused:UNUSED_PAD src0_sel:WORD_1 src1_sel:DWORD
	v_and_b32_sdwa v134, v89, v185 dst_sel:DWORD dst_unused:UNUSED_PAD src0_sel:WORD_1 src1_sel:DWORD
	v_and_b32_sdwa v132, v88, v185 dst_sel:DWORD dst_unused:UNUSED_PAD src0_sel:WORD_1 src1_sel:DWORD
	v_add3_u32 v133, v91, v133, s46
	v_add3_u32 v134, v89, v134, s46
	v_add3_u32 v132, v88, v132, s46
	v_and_b32_e32 v133, 0xffff0000, v133
	v_and_b32_e32 v134, 0xffff0000, v134
	v_and_b32_sdwa v135, v95, v185 dst_sel:DWORD dst_unused:UNUSED_PAD src0_sel:WORD_1 src1_sel:DWORD
	v_and_b32_sdwa v137, v93, v185 dst_sel:DWORD dst_unused:UNUSED_PAD src0_sel:WORD_1 src1_sel:DWORD
	v_or_b32_sdwa v133, v133, v0 dst_sel:DWORD dst_unused:UNUSED_PAD src0_sel:DWORD src1_sel:WORD_1
	v_or_b32_sdwa v132, v134, v132 dst_sel:DWORD dst_unused:UNUSED_PAD src0_sel:DWORD src1_sel:WORD_1
	v_and_b32_sdwa v0, v94, v185 dst_sel:DWORD dst_unused:UNUSED_PAD src0_sel:WORD_1 src1_sel:DWORD
	v_and_b32_sdwa v134, v92, v185 dst_sel:DWORD dst_unused:UNUSED_PAD src0_sel:WORD_1 src1_sel:DWORD
	v_add3_u32 v135, v95, v135, s46
	v_add3_u32 v137, v93, v137, s46
	v_add3_u32 v134, v92, v134, s46
	v_add3_u32 v0, v94, v0, s46
	v_and_b32_e32 v135, 0xffff0000, v135
	v_and_b32_e32 v137, 0xffff0000, v137
	v_or_b32_sdwa v135, v135, v0 dst_sel:DWORD dst_unused:UNUSED_PAD src0_sel:DWORD src1_sel:WORD_1
	v_or_b32_sdwa v134, v137, v134 dst_sel:DWORD dst_unused:UNUSED_PAD src0_sel:DWORD src1_sel:WORD_1
	global_store_dwordx4 v[140:141], v[132:135], off offset:256
	v_and_b32_sdwa v0, v66, v185 dst_sel:DWORD dst_unused:UNUSED_PAD src0_sel:WORD_1 src1_sel:DWORD
	v_add3_u32 v0, v66, v0, s46
	v_or_b32_e32 v132, 32, v136
	v_ashrrev_i32_e32 v133, 31, v132
	v_lshlrev_b64 v[132:133], 11, v[132:133]
	v_lshl_add_u64 v[140:141], v[138:139], 0, v[132:133]
	v_and_b32_sdwa v133, v67, v185 dst_sel:DWORD dst_unused:UNUSED_PAD src0_sel:WORD_1 src1_sel:DWORD
	v_and_b32_sdwa v134, v65, v185 dst_sel:DWORD dst_unused:UNUSED_PAD src0_sel:WORD_1 src1_sel:DWORD
	v_and_b32_sdwa v132, v64, v185 dst_sel:DWORD dst_unused:UNUSED_PAD src0_sel:WORD_1 src1_sel:DWORD
	v_add3_u32 v133, v67, v133, s46
	v_add3_u32 v134, v65, v134, s46
	v_add3_u32 v132, v64, v132, s46
	v_and_b32_e32 v133, 0xffff0000, v133
	v_and_b32_e32 v134, 0xffff0000, v134
	v_and_b32_sdwa v135, v71, v185 dst_sel:DWORD dst_unused:UNUSED_PAD src0_sel:WORD_1 src1_sel:DWORD
	v_and_b32_sdwa v137, v69, v185 dst_sel:DWORD dst_unused:UNUSED_PAD src0_sel:WORD_1 src1_sel:DWORD
; __device__ __forceinline__ unsigned pack2(float lo, float hi) { return (unsigned)f2bf(lo) | ((unsigned)f2bf(hi) << 16); }
;     __device__ __forceinline__ void operator()(const f32x4 (&acc)[2][2][4][2], const Unit& u, int wr, int wc, int fr, int fq) const {
;         EPIP_ROWS( uint4 o; o.x = pack2(v0[0], v0[1]); o.y = pack2(v0[2], v0[3]); o.z = pack2(v1[0], v1[1]); o.w = pack2(v1[2], v1[3]); *(uint4*)(O + row * ldc + col8 + co) = o; )
;     }
	v_or_b32_sdwa v133, v133, v0 dst_sel:DWORD dst_unused:UNUSED_PAD src0_sel:DWORD src1_sel:WORD_1
	v_or_b32_sdwa v132, v134, v132 dst_sel:DWORD dst_unused:UNUSED_PAD src0_sel:DWORD src1_sel:WORD_1
	v_and_b32_sdwa v0, v70, v185 dst_sel:DWORD dst_unused:UNUSED_PAD src0_sel:WORD_1 src1_sel:DWORD
	v_and_b32_sdwa v134, v68, v185 dst_sel:DWORD dst_unused:UNUSED_PAD src0_sel:WORD_1 src1_sel:DWORD
	v_add3_u32 v135, v71, v135, s46
	v_add3_u32 v137, v69, v137, s46
	v_add3_u32 v134, v68, v134, s46
	v_add3_u32 v0, v70, v0, s46
	v_and_b32_e32 v135, 0xffff0000, v135
	v_and_b32_e32 v137, 0xffff0000, v137
	v_or_b32_sdwa v135, v135, v0 dst_sel:DWORD dst_unused:UNUSED_PAD src0_sel:DWORD src1_sel:WORD_1
	v_or_b32_sdwa v134, v137, v134 dst_sel:DWORD dst_unused:UNUSED_PAD src0_sel:DWORD src1_sel:WORD_1
	global_store_dwordx4 v[140:141], v[132:135], off
	v_and_b32_sdwa v0, v98, v185 dst_sel:DWORD dst_unused:UNUSED_PAD src0_sel:WORD_1 src1_sel:DWORD
	v_add3_u32 v0, v98, v0, s46
	v_and_b32_sdwa v133, v99, v185 dst_sel:DWORD dst_unused:UNUSED_PAD src0_sel:WORD_1 src1_sel:DWORD
	v_and_b32_sdwa v134, v97, v185 dst_sel:DWORD dst_unused:UNUSED_PAD src0_sel:WORD_1 src1_sel:DWORD
	v_and_b32_sdwa v132, v96, v185 dst_sel:DWORD dst_unused:UNUSED_PAD src0_sel:WORD_1 src1_sel:DWORD
	v_add3_u32 v133, v99, v133, s46
	v_add3_u32 v134, v97, v134, s46
	v_add3_u32 v132, v96, v132, s46
	v_and_b32_e32 v133, 0xffff0000, v133
	v_and_b32_e32 v134, 0xffff0000, v134
	v_and_b32_sdwa v135, v103, v185 dst_sel:DWORD dst_unused:UNUSED_PAD src0_sel:WORD_1 src1_sel:DWORD
	v_and_b32_sdwa v137, v101, v185 dst_sel:DWORD dst_unused:UNUSED_PAD src0_sel:WORD_1 src1_sel:DWORD
	v_or_b32_sdwa v133, v133, v0 dst_sel:DWORD dst_unused:UNUSED_PAD src0_sel:DWORD src1_sel:WORD_1
	v_or_b32_sdwa v132, v134, v132 dst_sel:DWORD dst_unused:UNUSED_PAD src0_sel:DWORD src1_sel:WORD_1
	v_and_b32_sdwa v0, v102, v185 dst_sel:DWORD dst_unused:UNUSED_PAD src0_sel:WORD_1 src1_sel:DWORD
	v_and_b32_sdwa v134, v100, v185 dst_sel:DWORD dst_unused:UNUSED_PAD src0_sel:WORD_1 src1_sel:DWORD
	v_add3_u32 v135, v103, v135, s46
	v_add3_u32 v137, v101, v137, s46
	v_add3_u32 v134, v100, v134, s46
	v_add3_u32 v0, v102, v0, s46
	v_and_b32_e32 v135, 0xffff0000, v135
	v_and_b32_e32 v137, 0xffff0000, v137
	v_or_b32_sdwa v135, v135, v0 dst_sel:DWORD dst_unused:UNUSED_PAD src0_sel:DWORD src1_sel:WORD_1
	v_or_b32_sdwa v134, v137, v134 dst_sel:DWORD dst_unused:UNUSED_PAD src0_sel:DWORD src1_sel:WORD_1
	global_store_dwordx4 v[140:141], v[132:135], off offset:256
	v_and_b32_sdwa v0, v74, v185 dst_sel:DWORD dst_unused:UNUSED_PAD src0_sel:WORD_1 src1_sel:DWORD
	v_add3_u32 v0, v74, v0, s46
	v_or_b32_e32 v132, 48, v136
	v_ashrrev_i32_e32 v133, 31, v132
	v_lshlrev_b64 v[132:133], 11, v[132:133]
	v_lshl_add_u64 v[136:137], v[138:139], 0, v[132:133]
	v_and_b32_sdwa v133, v75, v185 dst_sel:DWORD dst_unused:UNUSED_PAD src0_sel:WORD_1 src1_sel:DWORD
	v_and_b32_sdwa v134, v73, v185 dst_sel:DWORD dst_unused:UNUSED_PAD src0_sel:WORD_1 src1_sel:DWORD
	v_and_b32_sdwa v132, v72, v185 dst_sel:DWORD dst_unused:UNUSED_PAD src0_sel:WORD_1 src1_sel:DWORD
	v_add3_u32 v133, v75, v133, s46
	v_add3_u32 v134, v73, v134, s46
	v_add3_u32 v132, v72, v132, s46
	v_and_b32_e32 v133, 0xffff0000, v133
	v_and_b32_e32 v134, 0xffff0000, v134
	v_and_b32_sdwa v135, v79, v185 dst_sel:DWORD dst_unused:UNUSED_PAD src0_sel:WORD_1 src1_sel:DWORD
	v_and_b32_sdwa v138, v77, v185 dst_sel:DWORD dst_unused:UNUSED_PAD src0_sel:WORD_1 src1_sel:DWORD
	v_or_b32_sdwa v133, v133, v0 dst_sel:DWORD dst_unused:UNUSED_PAD src0_sel:DWORD src1_sel:WORD_1
	v_or_b32_sdwa v132, v134, v132 dst_sel:DWORD dst_unused:UNUSED_PAD src0_sel:DWORD src1_sel:WORD_1
	v_and_b32_sdwa v0, v78, v185 dst_sel:DWORD dst_unused:UNUSED_PAD src0_sel:WORD_1 src1_sel:DWORD
	v_and_b32_sdwa v134, v76, v185 dst_sel:DWORD dst_unused:UNUSED_PAD src0_sel:WORD_1 src1_sel:DWORD
	v_add3_u32 v135, v79, v135, s46
	v_add3_u32 v138, v77, v138, s46
	v_add3_u32 v134, v76, v134, s46
	v_add3_u32 v0, v78, v0, s46
	v_and_b32_e32 v135, 0xffff0000, v135
	v_and_b32_e32 v138, 0xffff0000, v138
	v_or_b32_sdwa v135, v135, v0 dst_sel:DWORD dst_unused:UNUSED_PAD src0_sel:DWORD src1_sel:WORD_1
	v_or_b32_sdwa v134, v138, v134 dst_sel:DWORD dst_unused:UNUSED_PAD src0_sel:DWORD src1_sel:WORD_1
	global_store_dwordx4 v[136:137], v[132:135], off
	v_and_b32_sdwa v0, v106, v185 dst_sel:DWORD dst_unused:UNUSED_PAD src0_sel:WORD_1 src1_sel:DWORD
	v_add3_u32 v0, v106, v0, s46
	v_and_b32_sdwa v133, v107, v185 dst_sel:DWORD dst_unused:UNUSED_PAD src0_sel:WORD_1 src1_sel:DWORD
	v_and_b32_sdwa v134, v105, v185 dst_sel:DWORD dst_unused:UNUSED_PAD src0_sel:WORD_1 src1_sel:DWORD
	v_and_b32_sdwa v132, v104, v185 dst_sel:DWORD dst_unused:UNUSED_PAD src0_sel:WORD_1 src1_sel:DWORD
	v_add3_u32 v133, v107, v133, s46
	v_add3_u32 v134, v105, v134, s46
	v_add3_u32 v132, v104, v132, s46
	v_and_b32_e32 v133, 0xffff0000, v133
	v_and_b32_e32 v134, 0xffff0000, v134
	v_and_b32_sdwa v135, v111, v185 dst_sel:DWORD dst_unused:UNUSED_PAD src0_sel:WORD_1 src1_sel:DWORD
	v_and_b32_sdwa v138, v109, v185 dst_sel:DWORD dst_unused:UNUSED_PAD src0_sel:WORD_1 src1_sel:DWORD
	v_or_b32_sdwa v133, v133, v0 dst_sel:DWORD dst_unused:UNUSED_PAD src0_sel:DWORD src1_sel:WORD_1
	v_or_b32_sdwa v132, v134, v132 dst_sel:DWORD dst_unused:UNUSED_PAD src0_sel:DWORD src1_sel:WORD_1
	v_and_b32_sdwa v0, v110, v185 dst_sel:DWORD dst_unused:UNUSED_PAD src0_sel:WORD_1 src1_sel:DWORD
	v_and_b32_sdwa v134, v108, v185 dst_sel:DWORD dst_unused:UNUSED_PAD src0_sel:WORD_1 src1_sel:DWORD
	v_add3_u32 v135, v111, v135, s46
	v_add3_u32 v138, v109, v138, s46
	v_add3_u32 v134, v108, v134, s46
	v_add3_u32 v0, v110, v0, s46
; __device__ __forceinline__ unsigned pack2(float lo, float hi) { return (unsigned)f2bf(lo) | ((unsigned)f2bf(hi) << 16); }
;     __device__ __forceinline__ void operator()(const f32x4 (&acc)[2][2][4][2], const Unit& u, int wr, int wc, int fr, int fq) const {
;         EPIP_ROWS( uint4 o; o.x = pack2(v0[0], v0[1]); o.y = pack2(v0[2], v0[3]); o.z = pack2(v1[0], v1[1]); o.w = pack2(v1[2], v1[3]); *(uint4*)(O + row * ldc + col8 + co) = o; )
;     }
	v_and_b32_e32 v135, 0xffff0000, v135
	v_and_b32_e32 v138, 0xffff0000, v138
	v_or_b32_sdwa v135, v135, v0 dst_sel:DWORD dst_unused:UNUSED_PAD src0_sel:DWORD src1_sel:WORD_1
	v_or_b32_sdwa v134, v138, v134 dst_sel:DWORD dst_unused:UNUSED_PAD src0_sel:DWORD src1_sel:WORD_1
	global_store_dwordx4 v[136:137], v[132:135], off offset:256
	v_and_b32_sdwa v0, v114, v185 dst_sel:DWORD dst_unused:UNUSED_PAD src0_sel:WORD_1 src1_sel:DWORD
	v_and_b32_sdwa v138, v117, v185 dst_sel:DWORD dst_unused:UNUSED_PAD src0_sel:WORD_1 src1_sel:DWORD
	v_and_b32_sdwa v134, v113, v185 dst_sel:DWORD dst_unused:UNUSED_PAD src0_sel:WORD_1 src1_sel:DWORD
	v_and_b32_sdwa v132, v112, v185 dst_sel:DWORD dst_unused:UNUSED_PAD src0_sel:WORD_1 src1_sel:DWORD
	v_and_b32_sdwa v133, v115, v185 dst_sel:DWORD dst_unused:UNUSED_PAD src0_sel:WORD_1 src1_sel:DWORD
	v_add3_u32 v134, v113, v134, s46
	v_add3_u32 v132, v112, v132, s46
	v_add3_u32 v133, v115, v133, s46
	v_and_b32_e32 v134, 0xffff0000, v134
	s_mov_b64 s[12:13], 0x40000
	v_add3_u32 v0, v114, v0, s46
	v_and_b32_e32 v133, 0xffff0000, v133
	v_or_b32_sdwa v132, v134, v132 dst_sel:DWORD dst_unused:UNUSED_PAD src0_sel:DWORD src1_sel:WORD_1
	v_and_b32_sdwa v134, v116, v185 dst_sel:DWORD dst_unused:UNUSED_PAD src0_sel:WORD_1 src1_sel:DWORD
	v_and_b32_sdwa v135, v119, v185 dst_sel:DWORD dst_unused:UNUSED_PAD src0_sel:WORD_1 src1_sel:DWORD
	v_add3_u32 v138, v117, v138, s46
	v_lshl_add_u64 v[136:137], v[2:3], 0, s[12:13]
	v_or_b32_sdwa v133, v133, v0 dst_sel:DWORD dst_unused:UNUSED_PAD src0_sel:DWORD src1_sel:WORD_1
	v_and_b32_sdwa v0, v118, v185 dst_sel:DWORD dst_unused:UNUSED_PAD src0_sel:WORD_1 src1_sel:DWORD
	v_add3_u32 v134, v116, v134, s46
	v_add3_u32 v135, v119, v135, s46
	v_and_b32_e32 v138, 0xffff0000, v138
	s_mov_b32 s12, 0x40000
	v_add3_u32 v0, v118, v0, s46
	v_and_b32_e32 v135, 0xffff0000, v135
	v_or_b32_sdwa v134, v138, v134 dst_sel:DWORD dst_unused:UNUSED_PAD src0_sel:DWORD src1_sel:WORD_1
	v_add_co_u32_e32 v138, vcc, s12, v2
	v_or_b32_sdwa v135, v135, v0 dst_sel:DWORD dst_unused:UNUSED_PAD src0_sel:DWORD src1_sel:WORD_1
	s_nop 0
	v_addc_co_u32_e32 v139, vcc, 0, v3, vcc
	global_store_dwordx4 v[138:139], v[132:135], off
	v_and_b32_sdwa v0, v6, v185 dst_sel:DWORD dst_unused:UNUSED_PAD src0_sel:WORD_1 src1_sel:DWORD
	v_add3_u32 v0, v6, v0, s46
	v_and_b32_sdwa v133, v7, v185 dst_sel:DWORD dst_unused:UNUSED_PAD src0_sel:WORD_1 src1_sel:DWORD
	v_and_b32_sdwa v134, v5, v185 dst_sel:DWORD dst_unused:UNUSED_PAD src0_sel:WORD_1 src1_sel:DWORD
	v_and_b32_sdwa v132, v4, v185 dst_sel:DWORD dst_unused:UNUSED_PAD src0_sel:WORD_1 src1_sel:DWORD
	v_add3_u32 v133, v7, v133, s46
	v_add3_u32 v134, v5, v134, s46
	v_add3_u32 v132, v4, v132, s46
	v_and_b32_e32 v133, 0xffff0000, v133
	v_and_b32_e32 v134, 0xffff0000, v134
	v_and_b32_sdwa v135, v11, v185 dst_sel:DWORD dst_unused:UNUSED_PAD src0_sel:WORD_1 src1_sel:DWORD
	v_and_b32_sdwa v138, v9, v185 dst_sel:DWORD dst_unused:UNUSED_PAD src0_sel:WORD_1 src1_sel:DWORD
	v_or_b32_sdwa v133, v133, v0 dst_sel:DWORD dst_unused:UNUSED_PAD src0_sel:DWORD src1_sel:WORD_1
	v_or_b32_sdwa v132, v134, v132 dst_sel:DWORD dst_unused:UNUSED_PAD src0_sel:DWORD src1_sel:WORD_1
	v_and_b32_sdwa v0, v10, v185 dst_sel:DWORD dst_unused:UNUSED_PAD src0_sel:WORD_1 src1_sel:DWORD
	v_and_b32_sdwa v134, v8, v185 dst_sel:DWORD dst_unused:UNUSED_PAD src0_sel:WORD_1 src1_sel:DWORD
	v_add3_u32 v135, v11, v135, s46
	v_add3_u32 v138, v9, v138, s46
	v_add3_u32 v134, v8, v134, s46
	v_add3_u32 v0, v10, v0, s46
	v_and_b32_e32 v135, 0xffff0000, v135
	v_and_b32_e32 v138, 0xffff0000, v138
	v_or_b32_sdwa v135, v135, v0 dst_sel:DWORD dst_unused:UNUSED_PAD src0_sel:DWORD src1_sel:WORD_1
	v_or_b32_sdwa v134, v138, v134 dst_sel:DWORD dst_unused:UNUSED_PAD src0_sel:DWORD src1_sel:WORD_1
	global_store_dwordx4 v[136:137], v[132:135], off offset:256
	v_and_b32_sdwa v0, v122, v185 dst_sel:DWORD dst_unused:UNUSED_PAD src0_sel:WORD_1 src1_sel:DWORD
	v_and_b32_sdwa v138, v125, v185 dst_sel:DWORD dst_unused:UNUSED_PAD src0_sel:WORD_1 src1_sel:DWORD
	v_and_b32_sdwa v134, v121, v185 dst_sel:DWORD dst_unused:UNUSED_PAD src0_sel:WORD_1 src1_sel:DWORD
	v_and_b32_sdwa v132, v120, v185 dst_sel:DWORD dst_unused:UNUSED_PAD src0_sel:WORD_1 src1_sel:DWORD
	v_and_b32_sdwa v133, v123, v185 dst_sel:DWORD dst_unused:UNUSED_PAD src0_sel:WORD_1 src1_sel:DWORD
	v_add3_u32 v134, v121, v134, s46
	v_add3_u32 v132, v120, v132, s46
	v_add3_u32 v133, v123, v133, s46
	v_and_b32_e32 v134, 0xffff0000, v134
	s_mov_b64 s[12:13], 0x48000
	v_add3_u32 v0, v122, v0, s46
	v_and_b32_e32 v133, 0xffff0000, v133
	v_or_b32_sdwa v132, v134, v132 dst_sel:DWORD dst_unused:UNUSED_PAD src0_sel:DWORD src1_sel:WORD_1
	v_and_b32_sdwa v134, v124, v185 dst_sel:DWORD dst_unused:UNUSED_PAD src0_sel:WORD_1 src1_sel:DWORD
	v_and_b32_sdwa v135, v127, v185 dst_sel:DWORD dst_unused:UNUSED_PAD src0_sel:WORD_1 src1_sel:DWORD
	v_add3_u32 v138, v125, v138, s46
	v_lshl_add_u64 v[136:137], v[2:3], 0, s[12:13]
	v_or_b32_sdwa v133, v133, v0 dst_sel:DWORD dst_unused:UNUSED_PAD src0_sel:DWORD src1_sel:WORD_1
	v_and_b32_sdwa v0, v126, v185 dst_sel:DWORD dst_unused:UNUSED_PAD src0_sel:WORD_1 src1_sel:DWORD
	v_add3_u32 v134, v124, v134, s46
	v_add3_u32 v135, v127, v135, s46
	v_and_b32_e32 v138, 0xffff0000, v138
	s_mov_b32 s12, 0x48000
	v_add3_u32 v0, v126, v0, s46
	v_and_b32_e32 v135, 0xffff0000, v135
	v_or_b32_sdwa v134, v138, v134 dst_sel:DWORD dst_unused:UNUSED_PAD src0_sel:DWORD src1_sel:WORD_1
	v_add_co_u32_e32 v138, vcc, s12, v2
	v_or_b32_sdwa v135, v135, v0 dst_sel:DWORD dst_unused:UNUSED_PAD src0_sel:DWORD src1_sel:WORD_1
	s_nop 0
	v_addc_co_u32_e32 v139, vcc, 0, v3, vcc
	global_store_dwordx4 v[138:139], v[132:135], off
; __device__ __forceinline__ unsigned pack2(float lo, float hi) { return (unsigned)f2bf(lo) | ((unsigned)f2bf(hi) << 16); }
;     __device__ __forceinline__ void operator()(const f32x4 (&acc)[2][2][4][2], const Unit& u, int wr, int wc, int fr, int fq) const {
;         EPIP_ROWS( uint4 o; o.x = pack2(v0[0], v0[1]); o.y = pack2(v0[2], v0[3]); o.z = pack2(v1[0], v1[1]); o.w = pack2(v1[2], v1[3]); *(uint4*)(O + row * ldc + col8 + co) = o; )
;     }
	v_and_b32_sdwa v0, v14, v185 dst_sel:DWORD dst_unused:UNUSED_PAD src0_sel:WORD_1 src1_sel:DWORD
	v_add3_u32 v0, v14, v0, s46
	v_and_b32_sdwa v133, v15, v185 dst_sel:DWORD dst_unused:UNUSED_PAD src0_sel:WORD_1 src1_sel:DWORD
	v_and_b32_sdwa v134, v13, v185 dst_sel:DWORD dst_unused:UNUSED_PAD src0_sel:WORD_1 src1_sel:DWORD
	v_and_b32_sdwa v132, v12, v185 dst_sel:DWORD dst_unused:UNUSED_PAD src0_sel:WORD_1 src1_sel:DWORD
	v_add3_u32 v133, v15, v133, s46
	v_add3_u32 v134, v13, v134, s46
	v_add3_u32 v132, v12, v132, s46
	v_and_b32_e32 v133, 0xffff0000, v133
	v_and_b32_e32 v134, 0xffff0000, v134
	v_and_b32_sdwa v135, v19, v185 dst_sel:DWORD dst_unused:UNUSED_PAD src0_sel:WORD_1 src1_sel:DWORD
	v_and_b32_sdwa v138, v17, v185 dst_sel:DWORD dst_unused:UNUSED_PAD src0_sel:WORD_1 src1_sel:DWORD
	v_or_b32_sdwa v133, v133, v0 dst_sel:DWORD dst_unused:UNUSED_PAD src0_sel:DWORD src1_sel:WORD_1
	v_or_b32_sdwa v132, v134, v132 dst_sel:DWORD dst_unused:UNUSED_PAD src0_sel:DWORD src1_sel:WORD_1
	v_and_b32_sdwa v0, v18, v185 dst_sel:DWORD dst_unused:UNUSED_PAD src0_sel:WORD_1 src1_sel:DWORD
	v_and_b32_sdwa v134, v16, v185 dst_sel:DWORD dst_unused:UNUSED_PAD src0_sel:WORD_1 src1_sel:DWORD
	v_add3_u32 v135, v19, v135, s46
	v_add3_u32 v138, v17, v138, s46
	v_add3_u32 v134, v16, v134, s46
	v_add3_u32 v0, v18, v0, s46
	v_and_b32_e32 v135, 0xffff0000, v135
	v_and_b32_e32 v138, 0xffff0000, v138
	v_or_b32_sdwa v135, v135, v0 dst_sel:DWORD dst_unused:UNUSED_PAD src0_sel:DWORD src1_sel:WORD_1
	v_or_b32_sdwa v134, v138, v134 dst_sel:DWORD dst_unused:UNUSED_PAD src0_sel:DWORD src1_sel:WORD_1
	global_store_dwordx4 v[136:137], v[132:135], off offset:256
	v_and_b32_sdwa v0, v130, v185 dst_sel:DWORD dst_unused:UNUSED_PAD src0_sel:WORD_1 src1_sel:DWORD
	v_and_b32_sdwa v138, v37, v185 dst_sel:DWORD dst_unused:UNUSED_PAD src0_sel:WORD_1 src1_sel:DWORD
	v_and_b32_sdwa v134, v129, v185 dst_sel:DWORD dst_unused:UNUSED_PAD src0_sel:WORD_1 src1_sel:DWORD
	v_and_b32_sdwa v132, v128, v185 dst_sel:DWORD dst_unused:UNUSED_PAD src0_sel:WORD_1 src1_sel:DWORD
	v_and_b32_sdwa v133, v131, v185 dst_sel:DWORD dst_unused:UNUSED_PAD src0_sel:WORD_1 src1_sel:DWORD
	v_add3_u32 v134, v129, v134, s46
	v_add3_u32 v132, v128, v132, s46
	v_add3_u32 v133, v131, v133, s46
	v_and_b32_e32 v134, 0xffff0000, v134
	s_mov_b64 s[12:13], 0x50000
	v_add3_u32 v0, v130, v0, s46
	v_and_b32_e32 v133, 0xffff0000, v133
	v_or_b32_sdwa v132, v134, v132 dst_sel:DWORD dst_unused:UNUSED_PAD src0_sel:DWORD src1_sel:WORD_1
	v_and_b32_sdwa v134, v36, v185 dst_sel:DWORD dst_unused:UNUSED_PAD src0_sel:WORD_1 src1_sel:DWORD
	v_and_b32_sdwa v135, v39, v185 dst_sel:DWORD dst_unused:UNUSED_PAD src0_sel:WORD_1 src1_sel:DWORD
	v_add3_u32 v138, v37, v138, s46
	v_lshl_add_u64 v[136:137], v[2:3], 0, s[12:13]
	v_or_b32_sdwa v133, v133, v0 dst_sel:DWORD dst_unused:UNUSED_PAD src0_sel:DWORD src1_sel:WORD_1
	v_and_b32_sdwa v0, v38, v185 dst_sel:DWORD dst_unused:UNUSED_PAD src0_sel:WORD_1 src1_sel:DWORD
	v_add3_u32 v134, v36, v134, s46
	v_add3_u32 v135, v39, v135, s46
	v_and_b32_e32 v138, 0xffff0000, v138
	s_mov_b32 s12, 0x50000
	v_add3_u32 v0, v38, v0, s46
	v_and_b32_e32 v135, 0xffff0000, v135
	v_or_b32_sdwa v134, v138, v134 dst_sel:DWORD dst_unused:UNUSED_PAD src0_sel:DWORD src1_sel:WORD_1
	v_add_co_u32_e32 v138, vcc, s12, v2
	v_or_b32_sdwa v135, v135, v0 dst_sel:DWORD dst_unused:UNUSED_PAD src0_sel:DWORD src1_sel:WORD_1
	s_nop 0
	v_addc_co_u32_e32 v139, vcc, 0, v3, vcc
	global_store_dwordx4 v[138:139], v[132:135], off
	v_and_b32_sdwa v0, v22, v185 dst_sel:DWORD dst_unused:UNUSED_PAD src0_sel:WORD_1 src1_sel:DWORD
	v_add3_u32 v0, v22, v0, s46
	v_and_b32_sdwa v133, v23, v185 dst_sel:DWORD dst_unused:UNUSED_PAD src0_sel:WORD_1 src1_sel:DWORD
	v_and_b32_sdwa v134, v21, v185 dst_sel:DWORD dst_unused:UNUSED_PAD src0_sel:WORD_1 src1_sel:DWORD
	v_and_b32_sdwa v132, v20, v185 dst_sel:DWORD dst_unused:UNUSED_PAD src0_sel:WORD_1 src1_sel:DWORD
	v_add3_u32 v133, v23, v133, s46
	v_add3_u32 v134, v21, v134, s46
	v_add3_u32 v132, v20, v132, s46
	v_and_b32_e32 v133, 0xffff0000, v133
	v_and_b32_e32 v134, 0xffff0000, v134
	v_and_b32_sdwa v135, v27, v185 dst_sel:DWORD dst_unused:UNUSED_PAD src0_sel:WORD_1 src1_sel:DWORD
	v_and_b32_sdwa v138, v25, v185 dst_sel:DWORD dst_unused:UNUSED_PAD src0_sel:WORD_1 src1_sel:DWORD
; __device__ __forceinline__ unsigned pack2(float lo, float hi) { return (unsigned)f2bf(lo) | ((unsigned)f2bf(hi) << 16); }
;     __device__ __forceinline__ void operator()(const f32x4 (&acc)[2][2][4][2], const Unit& u, int wr, int wc, int fr, int fq) const {
;         EPIP_ROWS( uint4 o; o.x = pack2(v0[0], v0[1]); o.y = pack2(v0[2], v0[3]); o.z = pack2(v1[0], v1[1]); o.w = pack2(v1[2], v1[3]); *(uint4*)(O + row * ldc + col8 + co) = o; )
;     }
	v_or_b32_sdwa v133, v133, v0 dst_sel:DWORD dst_unused:UNUSED_PAD src0_sel:DWORD src1_sel:WORD_1
	v_or_b32_sdwa v132, v134, v132 dst_sel:DWORD dst_unused:UNUSED_PAD src0_sel:DWORD src1_sel:WORD_1
	v_and_b32_sdwa v0, v26, v185 dst_sel:DWORD dst_unused:UNUSED_PAD src0_sel:WORD_1 src1_sel:DWORD
	v_and_b32_sdwa v134, v24, v185 dst_sel:DWORD dst_unused:UNUSED_PAD src0_sel:WORD_1 src1_sel:DWORD
	v_add3_u32 v135, v27, v135, s46
	v_add3_u32 v138, v25, v138, s46
	v_add3_u32 v134, v24, v134, s46
	v_add3_u32 v0, v26, v0, s46
	v_and_b32_e32 v135, 0xffff0000, v135
	v_and_b32_e32 v138, 0xffff0000, v138
	v_or_b32_sdwa v135, v135, v0 dst_sel:DWORD dst_unused:UNUSED_PAD src0_sel:DWORD src1_sel:WORD_1
	v_or_b32_sdwa v134, v138, v134 dst_sel:DWORD dst_unused:UNUSED_PAD src0_sel:DWORD src1_sel:WORD_1
	global_store_dwordx4 v[136:137], v[132:135], off offset:256
	v_and_b32_sdwa v0, v42, v185 dst_sel:DWORD dst_unused:UNUSED_PAD src0_sel:WORD_1 src1_sel:DWORD
	s_mov_b64 s[12:13], 0x58000
	v_and_b32_sdwa v133, v43, v185 dst_sel:DWORD dst_unused:UNUSED_PAD src0_sel:WORD_1 src1_sel:DWORD
	v_and_b32_sdwa v134, v41, v185 dst_sel:DWORD dst_unused:UNUSED_PAD src0_sel:WORD_1 src1_sel:DWORD
	v_and_b32_sdwa v132, v40, v185 dst_sel:DWORD dst_unused:UNUSED_PAD src0_sel:WORD_1 src1_sel:DWORD
	v_add3_u32 v133, v43, v133, s46
	v_add3_u32 v134, v41, v134, s46
	v_add3_u32 v132, v40, v132, s46
	v_add3_u32 v0, v42, v0, s46
	v_and_b32_e32 v133, 0xffff0000, v133
	v_and_b32_e32 v134, 0xffff0000, v134
	v_and_b32_sdwa v135, v47, v185 dst_sel:DWORD dst_unused:UNUSED_PAD src0_sel:WORD_1 src1_sel:DWORD
	v_and_b32_sdwa v138, v45, v185 dst_sel:DWORD dst_unused:UNUSED_PAD src0_sel:WORD_1 src1_sel:DWORD
	v_lshl_add_u64 v[136:137], v[2:3], 0, s[12:13]
	v_or_b32_sdwa v133, v133, v0 dst_sel:DWORD dst_unused:UNUSED_PAD src0_sel:DWORD src1_sel:WORD_1
	v_or_b32_sdwa v132, v134, v132 dst_sel:DWORD dst_unused:UNUSED_PAD src0_sel:DWORD src1_sel:WORD_1
	v_and_b32_sdwa v0, v46, v185 dst_sel:DWORD dst_unused:UNUSED_PAD src0_sel:WORD_1 src1_sel:DWORD
	v_and_b32_sdwa v134, v44, v185 dst_sel:DWORD dst_unused:UNUSED_PAD src0_sel:WORD_1 src1_sel:DWORD
	v_add3_u32 v135, v47, v135, s46
	v_add3_u32 v138, v45, v138, s46
	s_mov_b32 s12, 0x58000
	v_add3_u32 v134, v44, v134, s46
	v_add3_u32 v0, v46, v0, s46
	v_and_b32_e32 v135, 0xffff0000, v135
	v_and_b32_e32 v138, 0xffff0000, v138
	v_add_co_u32_e32 v2, vcc, s12, v2
	v_or_b32_sdwa v135, v135, v0 dst_sel:DWORD dst_unused:UNUSED_PAD src0_sel:DWORD src1_sel:WORD_1
	v_or_b32_sdwa v134, v138, v134 dst_sel:DWORD dst_unused:UNUSED_PAD src0_sel:DWORD src1_sel:WORD_1
	v_addc_co_u32_e32 v3, vcc, 0, v3, vcc
	global_store_dwordx4 v[2:3], v[132:135], off
	v_and_b32_sdwa v3, v31, v185 dst_sel:DWORD dst_unused:UNUSED_PAD src0_sel:WORD_1 src1_sel:DWORD
	v_and_b32_sdwa v0, v30, v185 dst_sel:DWORD dst_unused:UNUSED_PAD src0_sel:WORD_1 src1_sel:DWORD
	v_and_b32_sdwa v132, v29, v185 dst_sel:DWORD dst_unused:UNUSED_PAD src0_sel:WORD_1 src1_sel:DWORD
	v_add3_u32 v3, v31, v3, s46
	v_and_b32_sdwa v2, v28, v185 dst_sel:DWORD dst_unused:UNUSED_PAD src0_sel:WORD_1 src1_sel:DWORD
	v_add3_u32 v0, v30, v0, s46
	v_add3_u32 v132, v29, v132, s46
	v_and_b32_e32 v3, 0xffff0000, v3
	v_add3_u32 v2, v28, v2, s46
	v_and_b32_e32 v132, 0xffff0000, v132
	v_or_b32_sdwa v133, v3, v0 dst_sel:DWORD dst_unused:UNUSED_PAD src0_sel:DWORD src1_sel:WORD_1
	v_and_b32_sdwa v3, v35, v185 dst_sel:DWORD dst_unused:UNUSED_PAD src0_sel:WORD_1 src1_sel:DWORD
	v_and_b32_sdwa v134, v33, v185 dst_sel:DWORD dst_unused:UNUSED_PAD src0_sel:WORD_1 src1_sel:DWORD
	v_or_b32_sdwa v132, v132, v2 dst_sel:DWORD dst_unused:UNUSED_PAD src0_sel:DWORD src1_sel:WORD_1
	v_and_b32_sdwa v0, v34, v185 dst_sel:DWORD dst_unused:UNUSED_PAD src0_sel:WORD_1 src1_sel:DWORD
	v_and_b32_sdwa v2, v32, v185 dst_sel:DWORD dst_unused:UNUSED_PAD src0_sel:WORD_1 src1_sel:DWORD
	v_add3_u32 v3, v35, v3, s46
	v_add3_u32 v134, v33, v134, s46
	v_add3_u32 v2, v32, v2, s46
	v_add3_u32 v0, v34, v0, s46
	v_and_b32_e32 v3, 0xffff0000, v3
	v_and_b32_e32 v134, 0xffff0000, v134
	v_or_b32_sdwa v135, v3, v0 dst_sel:DWORD dst_unused:UNUSED_PAD src0_sel:DWORD src1_sel:WORD_1
	v_or_b32_sdwa v134, v134, v2 dst_sel:DWORD dst_unused:UNUSED_PAD src0_sel:DWORD src1_sel:WORD_1
	global_store_dwordx4 v[136:137], v[132:135], off offset:256
	s_mov_b64 s[12:13], 0
	s_mov_b64 s[14:15], 0

; #define PG8_WAIT_V(n) asm volatile("s_waitcnt vmcnt(" #n ")" ::: "memory")
; #define PG8_BAR __builtin_amdgcn_s_barrier()
; template <class Epi>
; __device__ __forceinline__ void gemm_phase(LAS unsigned char* lds, const Gemm g, const Epi& E) {
;     ...
;     PG8_WAIT_V(0);
;     if (wr == 0) PG8_BAR;
;     PG8_BAR;
.LBB0_357:
	s_setprio 0
	s_waitcnt vmcnt(0)
	v_readlane_b32 s0, v249, 58
	v_readlane_b32 s18, v249, 52
	v_readlane_b32 s20, v249, 56
	s_cmpk_gt_u32 s0, 0xff
	v_readlane_b32 s64, v249, 11
	s_movk_i32 s78, 0xffe0
	v_readlane_b32 s81, v249, 51
	v_readlane_b32 s19, v249, 53
	v_readlane_b32 s21, v249, 57
	s_cbranch_scc1 .LBB0_213
	s_barrier
	s_branch .LBB0_213
